# phase-transition trims: leader releases XCD before its own L1 invalidate; census loads in flight together; RsOrder::build second pass skipped when 4G>=nwg; gate_up build issues 4th unit loads before f
# speedup vs baseline: 1.0061x; 1.0061x over previous
.LBB0_123:
	s_or_b64 exec, exec, s[12:13]
	s_xor_b64 s[12:13], s[10:11], -1
	s_lshl_b32 s20, s70, 2
	s_cmp_ge_u32 s20, s8
	s_cselect_b64 s[10:11], -1, 0
	s_or_b64 s[12:13], s[12:13], s[10:11]
	s_mov_b32 s20, 4
	s_mov_b64 s[10:11], 0
	s_and_b64 vcc, exec, s[12:13]
	s_cbranch_vccnz .LBB0_148

.LBB0_148:
	s_nop 0
	s_nop 0
	s_nop 0
	s_nop 0
	s_nop 0
	s_nop 0
	s_nop 0
	s_nop 0
	s_nop 0
	s_nop 0
	s_nop 0
	s_nop 0
	s_waitcnt lgkmcnt(0)
	s_barrier

.LBB0_232:
	s_nop 0
	s_nop 0
	s_nop 0
	s_nop 0
	s_nop 0
	s_nop 0
	s_nop 0
	s_nop 0
	s_nop 0
	s_nop 0
	s_nop 0
	s_nop 0
	s_nop 0
	s_nop 0
	v_readlane_b32 s2, v254, 11
	v_readlane_b32 s3, v254, 12
	v_cmp_ne_u32_e32 vcc, 0, v1
	s_nop 0
	v_cndmask_b32_e64 v17, 0, v1, s[2:3]
	v_readlane_b32 s2, v254, 9
	v_readlane_b32 s3, v254, 10
	v_cndmask_b32_e64 v1, 0, 1, vcc
	v_cmp_ne_u32_e32 vcc, 0, v2
	v_cndmask_b32_e64 v17, v17, v2, s[2:3]
	v_readlane_b32 s2, v254, 7
	v_readlane_b32 s3, v254, 8
	v_addc_co_u32_e32 v1, vcc, 0, v1, vcc
	s_nop 0
	v_cndmask_b32_e64 v17, v17, v3, s[2:3]
	v_readlane_b32 s2, v254, 5
	v_readlane_b32 s3, v254, 6
	v_cmp_ne_u32_e32 vcc, 0, v3
	s_nop 0
	v_cndmask_b32_e64 v17, v17, v4, s[2:3]
	v_readlane_b32 s2, v254, 3
	v_readlane_b32 s3, v254, 4
	v_cndmask_b32_e64 v2, 0, 1, vcc
	v_cmp_ne_u32_e32 vcc, 0, v4
	v_cndmask_b32_e64 v17, v17, v5, s[2:3]
	v_readlane_b32 s2, v254, 1
	v_readlane_b32 s3, v254, 2
	v_addc_co_u32_e32 v1, vcc, v1, v2, vcc
	s_nop 0
	v_cndmask_b32_e64 v17, v17, v6, s[2:3]
	v_readlane_b32 s2, v253, 63
	v_readlane_b32 s3, v254, 0
	v_cmp_ne_u32_e32 vcc, 0, v5
	s_nop 0
	v_cndmask_b32_e64 v17, v17, v7, s[2:3]
	v_readlane_b32 s2, v253, 61
	v_readlane_b32 s3, v253, 62
	v_cndmask_b32_e64 v2, 0, 1, vcc
	v_cmp_ne_u32_e32 vcc, 0, v6
	v_cndmask_b32_e64 v17, v17, v8, s[2:3]
	v_readlane_b32 s2, v253, 59
	v_readlane_b32 s3, v253, 60
	v_addc_co_u32_e32 v1, vcc, v1, v2, vcc
	s_nop 0
	v_cndmask_b32_e64 v17, v17, v9, s[2:3]
	v_readlane_b32 s2, v253, 57
	v_cmp_ne_u32_e32 vcc, 0, v7
	v_readlane_b32 s3, v253, 58
	s_nop 0
	v_cndmask_b32_e64 v2, 0, 1, vcc
	v_cmp_ne_u32_e32 vcc, 0, v8
	v_cndmask_b32_e64 v17, v17, v10, s[2:3]
	v_readlane_b32 s2, v253, 55
	v_addc_co_u32_e32 v1, vcc, v1, v2, vcc
	v_readlane_b32 s3, v253, 56
	v_cmp_ne_u32_e32 vcc, 0, v9
	s_nop 0
	v_cndmask_b32_e64 v17, v17, v11, s[2:3]
	v_readlane_b32 s2, v253, 53
	v_cndmask_b32_e64 v2, 0, 1, vcc
	v_cmp_ne_u32_e32 vcc, 0, v10
	v_readlane_b32 s3, v253, 54
	s_nop 0
	v_addc_co_u32_e32 v1, vcc, v1, v2, vcc
	v_cndmask_b32_e64 v17, v17, v12, s[2:3]
	v_readlane_b32 s2, v253, 51
	v_cmp_ne_u32_e32 vcc, 0, v11
	v_readlane_b32 s3, v253, 52
	s_nop 0
	v_cndmask_b32_e64 v2, 0, 1, vcc
	v_cmp_ne_u32_e32 vcc, 0, v12
	v_cndmask_b32_e64 v17, v17, v13, s[2:3]
	v_readlane_b32 s2, v253, 49
	v_addc_co_u32_e32 v1, vcc, v1, v2, vcc
	v_readlane_b32 s3, v253, 50
	v_cmp_ne_u32_e32 vcc, 0, v13
	s_nop 0
	v_cndmask_b32_e64 v17, v17, v14, s[2:3]
	v_readlane_b32 s2, v253, 47
	v_cndmask_b32_e64 v2, 0, 1, vcc
	v_cmp_ne_u32_e32 vcc, 0, v14
	v_readlane_b32 s3, v253, 48
	s_nop 0
	v_addc_co_u32_e32 v1, vcc, v1, v2, vcc
	v_cndmask_b32_e64 v17, v17, v15, s[2:3]
	v_readlane_b32 s2, v253, 45
	v_cmp_ne_u32_e32 vcc, 0, v15
	v_readlane_b32 s3, v253, 46
	s_nop 0
	v_cndmask_b32_e64 v2, 0, 1, vcc
	v_cmp_ne_u32_e32 vcc, 0, v16
	v_cndmask_b32_e64 v17, v17, v16, s[2:3]
	v_readlane_b32 s2, v254, 52
	v_addc_co_u32_e32 v1, vcc, v1, v2, vcc
	v_max_u32_e32 v3, 1, v17
	v_max_u32_e32 v2, 1, v1
	v_mov_b32_e32 v1, s2
	v_readlane_b32 s2, v254, 53
	ds_write_b32 v1, v3
	s_nop 0
	v_mov_b32_e32 v1, s2
	ds_write_b32 v1, v2

.LBB0_264:
	s_or_b64 exec, exec, s[4:5]
	v_readlane_b32 s2, v254, 15
	v_readlane_b32 s3, v254, 16
	s_waitcnt vmcnt(0)
	s_nop 3
	global_atomic_add v0, v234, s[2:3]
	buffer_inv sc1
	s_waitcnt vmcnt(0)

.LBB0_663:
	s_and_b64 s[8:9], s[34:35], s[8:9]
	s_and_b64 s[8:9], s[8:9], exec
	s_cselect_b32 s8, 0x80, 0
	v_cmp_lt_i64_e32 vcc, s[10:11], v[204:205]
	s_or_b32 s10, s12, s8
	s_and_b64 s[8:9], vcc, exec
	s_cselect_b32 s8, s10, 0
	v_add_u32_e32 v74, s8, v1
	v_ashrrev_i32_e32 v75, 31, v74
	v_lshlrev_b64 v[74:75], 7, v[74:75]
	v_lshl_add_u64 v[76:77], v[50:51], 0, v[74:75]
	global_load_dwordx4 v[58:61], v[76:77], off offset:48
	global_load_dwordx4 v[62:65], v[76:77], off offset:32
	global_load_dwordx4 v[66:69], v[76:77], off offset:16
	global_load_dwordx4 v[70:73], v[76:77], off
	s_waitcnt vmcnt(4)
	v_pk_add_f32 v[26:27], v[30:31], v[26:27]
	v_pk_add_f32 v[18:19], v[22:23], v[18:19]
	v_pk_add_f32 v[56:57], v[26:27], v[18:19]
	v_pk_add_f32 v[28:29], v[32:33], v[28:29]
	v_pk_add_f32 v[20:21], v[24:25], v[20:21]
	v_pk_add_f32 v[54:55], v[28:29], v[20:21]
	v_add_f32_e32 v56, v56, v57
	v_add_f32_e32 v54, v54, v55
	v_add_f32_e32 v55, v56, v54
	ds_bpermute_b32 v56, v52, v55
	v_lshl_add_u32 v54, s2, 10, v53
	s_and_saveexec_b64 s[8:9], s[38:39]
	s_cbranch_execz .LBB0_665
	s_waitcnt lgkmcnt(0)
	v_add_f32_e32 v55, v55, v56
	v_fmamk_f32 v55, v55, 0x3a000000, v233
	v_mul_f32_e32 v56, 0x4b800000, v55
	v_cmp_gt_f32_e32 vcc, s36, v55
	s_nop 1
	v_cndmask_b32_e32 v55, v55, v56, vcc
	v_rsq_f32_e32 v55, v55
	s_nop 0
	v_mul_f32_e32 v56, 0x45800000, v55
	v_cndmask_b32_e32 v55, v55, v56, vcc
	ds_write_b32 v54, v55

.LBB0_669:
	s_or_b64 exec, exec, s[8:9]
	s_waitcnt vmcnt(0) lgkmcnt(0)
	v_pk_add_f32 v[2:3], v[72:73], v[68:69]
	v_pk_add_f32 v[4:5], v[70:71], v[66:67]
	v_pk_add_f32 v[6:7], v[62:63], v[58:59]
	v_pk_add_f32 v[8:9], v[64:65], v[60:61]
	v_pk_add_f32 v[4:5], v[4:5], v[6:7]
	v_pk_add_f32 v[2:3], v[2:3], v[8:9]
	v_add_f32_e32 v4, v4, v5
	v_add_f32_e32 v2, v2, v3
	v_add_f32_e32 v2, v4, v2
	ds_bpermute_b32 v3, v52, v2
	s_and_saveexec_b64 s[8:9], s[38:39]
	s_cbranch_execz .LBB0_654
	s_waitcnt lgkmcnt(0)
	v_add_f32_e32 v2, v2, v3
	v_fmamk_f32 v2, v2, 0x3a000000, v233
	v_mul_f32_e32 v3, 0x4b800000, v2
	v_cmp_gt_f32_e32 vcc, s36, v2
	s_nop 1
	v_cndmask_b32_e32 v2, v2, v3, vcc
	v_rsq_f32_e32 v2, v2
	s_nop 0
	v_mul_f32_e32 v3, 0x45800000, v2
	v_cndmask_b32_e32 v2, v2, v3, vcc
	ds_write_b32 v54, v2 offset:3072
	s_branch .LBB0_654
.LBB0_671:
	s_nop 0
	v_readlane_b32 s6, v254, 32
	v_mov_b32_e32 v15, v232
	v_readlane_b32 s7, v254, 33
	s_waitcnt lgkmcnt(0)
	s_barrier
	s_and_b64 vcc, exec, s[6:7]
	v_readfirstlane_b32 s2, v15
	s_cbranch_vccz .LBB0_697
	v_lshlrev_b32_e32 v2, 4, v15
	v_add_u32_e32 v3, 0x2000, v2
	v_ashrrev_i32_e32 v1, 31, v3
	v_lshrrev_b32_e32 v1, 22, v1
	v_add_u32_e32 v1, v3, v1
	v_ashrrev_i32_e32 v1, 10, v1
	v_mul_i32_i24_e32 v4, 0x400, v1
	v_sub_u32_e32 v3, v3, v4
	v_lshrrev_b32_e32 v4, 4, v3
	v_bitop3_b32 v3, v4, v3, 32 bitop3:0x6c
	s_add_u32 s19, s0, 0x30e00000
	v_readlane_b32 s6, v255, 26
	v_ashrrev_i32_e32 v4, 31, v3
	s_addc_u32 s23, s1, 0
	s_ashr_i32 s12, s2, 6
	v_readlane_b32 s7, v255, 27
	s_mul_i32 s52, s6, 0x1600000
	v_lshrrev_b32_e32 v4, 26, v4
	s_ashr_i32 s3, s2, 8
	s_lshl_b32 s8, s12, 10
	s_lshl_b64 s[6:7], s[52:53], 1
	v_add_u32_e32 v4, v3, v4
	v_lshlrev_b32_e32 v5, 3, v1
	s_add_u32 s6, s0, s6
	v_ashrrev_i32_e32 v10, 6, v4
	v_and_b32_e32 v5, -16, v5
	s_addc_u32 s7, s1, s7
	v_add_u32_e32 v5, v10, v5
	s_add_u32 s29, s6, 0x6900000
	v_and_b32_e32 v6, 3, v10
	s_mov_b32 s6, 0xfffe0
	v_lshrrev_b32_e32 v7, 2, v5
	v_lshlrev_b32_e32 v8, 1, v5
	v_and_b32_e32 v4, 0xc0, v4
	v_and_or_b32 v6, v5, s6, v6
	v_and_b32_e32 v7, 4, v7
	v_and_b32_e32 v8, 24, v8
	v_sub_u32_e32 v3, v3, v4
	v_or3_b32 v6, v6, v7, v8
	v_lshlrev_b32_e32 v7, 5, v1
	v_ashrrev_i16_sdwa v3, v234, sext(v3) dst_sel:DWORD dst_unused:UNUSED_PAD src0_sel:DWORD src1_sel:BYTE_0
	v_and_b32_e32 v7, 32, v7
	v_bfe_i32 v11, v3, 0, 16
	v_add_lshl_u32 v3, v7, v11, 1
	v_lshl_add_u32 v208, v6, 12, v3
	v_lshl_add_u32 v210, v5, 12, v3
	v_bfe_i32 v3, v15, 27, 1
	v_lshrrev_b32_e32 v3, 22, v3
	v_add_u32_e32 v3, v2, v3
	v_and_b32_e32 v3, 0xfffffc00, v3
	v_sub_u32_e32 v2, v2, v3
	v_lshrrev_b32_e32 v3, 4, v2
	v_ashrrev_i32_e32 v4, 31, v15
	v_bitop3_b32 v2, v3, v2, 32 bitop3:0x6c
	v_lshrrev_b32_e32 v4, 26, v4
	v_ashrrev_i32_e32 v3, 31, v2
	v_add_u32_e32 v4, v15, v4
	v_lshrrev_b32_e32 v3, 26, v3
	v_ashrrev_i32_e32 v13, 6, v4
	v_add_u32_e32 v3, v2, v3
	v_lshlrev_b32_e32 v4, 3, v13
	v_ashrrev_i32_e32 v12, 6, v3
	v_and_b32_e32 v4, -16, v4
	v_add_u32_e32 v4, v12, v4
	v_and_b32_e32 v5, 3, v12
	s_addc_u32 s30, s7, 0
	v_and_or_b32 v5, v4, s6, v5
	v_readlane_b32 s6, v254, 41
	v_readlane_b32 s7, v254, 42
	s_add_u32 s16, s29, s6
	s_addc_u32 s17, s30, s7
	s_add_i32 s31, s8, 0
	v_lshrrev_b32_e32 v6, 2, v4
	v_lshlrev_b32_e32 v7, 1, v4
	v_and_b32_e32 v3, 0xc0, v3
	s_add_i32 s36, s31, 0x10000
	s_add_i32 s37, s31, 0x12000
	v_readlane_b32 s6, v254, 37
	v_and_b32_e32 v6, 4, v6
	v_and_b32_e32 v7, 24, v7
	v_sub_u32_e32 v2, v2, v3
	v_readlane_b32 s7, v254, 38
	s_add_u32 s6, s19, s6
	v_or3_b32 v5, v5, v6, v7
	v_lshlrev_b32_e32 v6, 5, v13
	v_ashrrev_i16_sdwa v2, v234, sext(v2) dst_sel:DWORD dst_unused:UNUSED_PAD src0_sel:DWORD src1_sel:BYTE_0
	s_addc_u32 s7, s23, s7
	v_readlane_b32 s8, v254, 40
	v_and_b32_e32 v6, 32, v6
	v_bfe_i32 v14, v2, 0, 16
	s_add_u32 s10, s6, s8
	v_add_lshl_u32 v2, v6, v14, 1
	s_addc_u32 s11, s7, 0
	v_lshl_add_u32 v212, v5, 12, v2
	s_mov_b32 m0, s36
	s_add_u32 s6, s16, 0x80000
	global_load_lds_dwordx4 v212, s[16:17]
	s_mov_b32 m0, s37
	s_addc_u32 s7, s17, 0
	s_add_i32 s48, s31, 0x14000
	global_load_lds_dwordx4 v208, s[16:17]
	s_mov_b32 m0, s48
	s_add_i32 s49, s31, 0x16000
	global_load_lds_dwordx4 v212, s[6:7]
	s_mov_b32 m0, s49
	s_add_i32 s50, s31, 0x2000
	global_load_lds_dwordx4 v208, s[6:7]
	v_readlane_b32 s6, v254, 45
	v_lshl_add_u32 v214, v4, 12, v2
	s_mov_b32 m0, s31
	v_readlane_b32 s7, v254, 46
	s_add_u32 s6, s10, s6
	global_load_lds_dwordx4 v214, s[10:11]
	s_mov_b32 m0, s50
	s_addc_u32 s7, s11, 0
	s_add_i32 s51, s31, 0x4000
	global_load_lds_dwordx4 v210, s[10:11]
	s_mov_b32 m0, s51
	s_add_i32 s60, s31, 0x6000
	global_load_lds_dwordx4 v214, s[6:7]
	s_mov_b32 m0, s60
	v_mov_b32_e32 v213, v0
	global_load_lds_dwordx4 v210, s[6:7]
	v_mov_b32_e32 v209, v0
	v_mov_b32_e32 v215, v0
	v_mov_b32_e32 v211, v0
	s_cmp_eq_u32 s3, 1
	s_movk_i32 s75, 0xb1
	v_lshl_add_u64 v[8:9], s[16:17], 0, v[212:213]
	v_lshl_add_u64 v[6:7], s[16:17], 0, v[208:209]
	v_lshl_add_u64 v[2:3], s[10:11], 0, v[214:215]
	s_cselect_b64 s[6:7], -1, 0
	s_cmp_lg_u32 s3, 1
	v_lshl_add_u64 v[4:5], s[10:11], 0, v[210:211]
	s_cbranch_scc1 .LBB0_674
	s_barrier

.LBB0_745:
	s_or_b64 exec, exec, s[6:7]
	v_readlane_b32 s2, v254, 15
	v_readlane_b32 s3, v254, 16
	s_waitcnt vmcnt(0)
	s_nop 3
	global_atomic_add v0, v234, s[2:3]
	buffer_inv sc1
	s_waitcnt vmcnt(0)
